# P1 K-loop: skip the first two vmcnt(8) waits of a unit that follows an epilogue (as in P6)
# baseline (speedup 1.0000x reference)
; #define PG8_WAIT_V(n) asm volatile("s_waitcnt vmcnt(" #n ")" ::: "memory")
;     __device__ __forceinline__ void operator()(const f32x4 (&acc)[2][2][4][2], const Unit& u, int wr, int wc, int fr, int fq) const {
;         const int pn = u.pn;
;         const int kind = pn >= 7 ? 0 : (pn >= 3 ? 1 : ((pn < 2 || wc < 2) ? 2 : 3));
;         const int i0 = kind == 1 ? 32 * (wc & 1) + 8 * fq : 8 * fq;
;         const int rbase = u.pm * BM + wr * 64 + fr;
;         const bool rope = kind == 1 || kind == 2;
;         float revf[8];
; #pragma unroll
;     const int tid = tid_of(wave0), wid = wave0, lane = tid & 63, wr = wid >> 2, wc = wid & 3, fr = lane & 15, fq = lane >> 4;
;     const int K = g.K;
;     unsigned voffA[2], voffB[2];
; #pragma unroll
;     for (int i = 0; i < 2; ++i) { int R, C; stage_rc(tid * 16 + i * 8192, R, C); const int Rb = (R >> 5) * 64 + (Epi::PERM ? perm32(R & 31) : (R & 31));
;         voffA[i] = (unsigned)(R * K + C) * 2u; voffB[i] = (unsigned)(Rb * K + C) * 2u; }
;     const size_t kstep = (size_t)(BK * 2);
;     const size_t hstep = (size_t)HALF * K * 2;
;     const size_t tstep = 2 * hstep;
;     const size_t hstepB = (size_t)32 * K * 2;
;     const unsigned ldsw = (unsigned)wid * 1024u;
;     const int aoff = lds_byte(wr * 64 + fr, fq * 8), boff = lds_byte(wc * 32 + fr, fq * 8);
;     ...
;     Unit cur, nxt; int ui = 0;
;     if (!S.next(0, cur)) return;
;     f32x4 acc[2][2][4][2];
; #pragma unroll
;     for (int a = 0; a < 2; ++a)
; #pragma unroll
;         for (int b = 0; b < 2; ++b)
; #pragma unroll
;             for (int m = 0; m < 4; ++m)
; #pragma unroll
;                 for (int n = 0; n < 2; ++n) acc[a][b][m][n] = (f32x4){0.f, 0.f, 0.f, 0.f};
;     bf16x8 At[4][2], B0[2][2], B1[2][2];
;     const char* cA = (const char*)g.A + (size_t)cur.pm * tstep + (size_t)cur.k0 * (BK * 2); const char* cB = (const char*)g.Bt + (size_t)cur.pn * tstep + (size_t)cur.k0 * (BK * 2);
;     S.a_ready(cur);
;     if constexpr (SP2) {
;         PG8_STAGE(PG8_SB(0, 0), cB, voffB); PG8_STAGE(PG8_SB(0, 1), cB + hstepB, voffB); PG8_STAGEA(PG8_SA(0, 0), cA, voffA); PG8_STAGEA(PG8_SA(0, 1), cA + hstep, voffA);
;         if (wr == 1) PG8_BAR;
;         PG8_WAIT_V(2); PG8_BAR;
;         PG8_STAGE(PG8_SB(1, 0), cB + kstep, voffB); PG8_STAGEA(PG8_SA(1, 0), cA + kstep, voffA); PG8_STAGE(PG8_SB(1, 1), cB + hstepB + kstep, voffB);
;         PG8_WAIT_V(6); PG8_BAR;
.LBB0_109:
	s_add_u32 s14, s68, 0x100000
	s_mov_b64 s[16:17], 0x80
	s_addc_u32 s15, s69, 0
	s_add_i32 m0, s85, 0x18000
	v_lshl_add_u64 v[4:5], v[4:5], 0, s[16:17]
	s_waitcnt vmcnt(2)
	s_barrier
	global_load_lds_dwordx4 v[4:5], off
	v_lshl_add_u64 v[2:3], v[2:3], 0, s[16:17]
	s_add_i32 m0, s85, 0x1a000
	s_add_i32 s89, s85, 0x8000
	s_add_i32 s90, s85, 0xa000
	global_load_lds_dwordx4 v[2:3], off
	v_lshl_add_u64 v[0:1], v[0:1], 0, s[16:17]
	s_mov_b32 m0, s89
	s_add_u32 s0, s36, 0x10080
	global_load_lds_dwordx4 v[0:1], off
	v_lshl_add_u64 v[0:1], v[6:7], 0, s[16:17]
	s_mov_b32 m0, s90
	s_addc_u32 s1, s37, 0
	global_load_lds_dwordx4 v[0:1], off
	s_add_i32 m0, s85, 0x1c000
	v_lshl_add_u64 v[0:1], s[0:1], 0, v[146:147]
	global_load_lds_dwordx4 v[0:1], off
	v_lshl_add_u64 v[0:1], s[0:1], 0, v[150:151]
	s_add_i32 m0, s85, 0x1e000
	v_and_b32_e32 v155, 15, v8
	global_load_lds_dwordx4 v[0:1], off
	v_lshrrev_b32_e32 v16, 1, v8
	v_or_b32_e32 v15, s72, v155
	v_and_b32_e32 v154, 24, v16
	v_lshlrev_b32_e32 v16, 6, v15
	v_lshlrev_b32_e32 v17, 1, v154
	s_movk_i32 s0, 0x3c0
	v_lshlrev_b32_e32 v1, 2, v15
	v_and_or_b32 v0, v16, s0, v17
	v_and_b32_e32 v1, 32, v1
	v_readlane_b32 s0, v255, 18
	v_sub_co_u32_e64 v156, s[20:21], s48, 2
	s_nop 0
	v_bitop3_b32 v4, v0, s0, v1 bitop3:0xde
	v_lshlrev_b32_e32 v1, 2, v8
	v_lshl_or_b32 v0, v155, 6, v17
	v_and_b32_e32 v1, 32, v1
	v_readlane_b32 s0, v255, 19
	v_ashrrev_i32_e32 v157, 31, v156
	v_lshlrev_b32_e32 v152, 2, v154
	v_bitop3_b32 v226, v0, s0, v1 bitop3:0xde
	v_readlane_b32 s0, v255, 10
	v_lshlrev_b64 v[0:1], 8, v[156:157]
	s_cmpk_lt_u32 s0, 0x100
	v_lshl_add_u64 v[2:3], s[62:63], 0, v[152:153]
	s_mov_b64 s[0:1], 0x4800000
	v_lshl_add_u64 v[0:1], s[62:63], 0, v[0:1]
	v_lshl_add_u64 v[160:161], v[2:3], 0, s[0:1]
	v_lshl_add_u64 v[0:1], v[0:1], 0, v[152:153]
	s_mov_b64 s[0:1], 0x4480000
	s_cselect_b64 s[18:19], -1, 0
	s_lshl_b32 s92, s48, 6
	v_lshl_add_u64 v[162:163], v[0:1], 0, s[0:1]
	v_lshlrev_b32_e32 v0, 14, v9
	s_and_b32 s91, s65, 32
	s_and_b32 s93, s92, 0x80
	s_or_b32 s94, s48, 0x80
	s_ashr_i32 s95, s96, 31
	s_ashr_i32 s97, s2, 31
	v_and_b32_e32 v0, 0xffff8000, v0
	s_add_u32 s22, s62, 0x4700000
	v_lshl_add_u32 v0, v10, 11, v0
	v_and_b32_e32 v1, 1, v9
	s_addc_u32 s23, s63, 0
	s_lshl_b32 s0, s48, 8
	v_lshl_or_b32 v0, v1, 6, v0
	s_add_u32 s0, s62, s0
	v_lshl_add_u32 v164, v11, 1, v0
	v_lshlrev_b32_e32 v0, 14, v12
	s_addc_u32 s1, s63, 0
	v_and_b32_e32 v0, 0xffff8000, v0
	s_waitcnt vmcnt(6)
	s_add_u32 s24, s0, 0x4400000
	v_lshl_add_u32 v0, v13, 11, v0
	v_and_b32_e32 v1, 1, v12
	v_lshlrev_b32_e32 v158, 6, v156
	s_addc_u32 s25, s1, 0
	v_lshl_or_b32 v0, v1, 6, v0
	s_add_i32 s73, 0, 0x10000
	s_add_i32 s46, 0, 0x14000
	v_or_b32_e32 v227, 0x800, v155
	v_ashrrev_i32_e32 v159, 31, v158
	v_or_b32_e32 v228, s92, v154
	v_mov_b32_e32 v165, v153
	v_lshl_add_u32 v166, v14, 1, v0
	v_mov_b32_e32 v167, v153
	v_mov_b64_e32 v[168:169], 0x2ec
	v_mov_b64_e32 v[170:171], 0x2eb
	v_add_u32_e32 v229, s73, v226
	v_add_u32_e32 v230, s46, v226
	v_add_u32_e32 v231, 0, v4
	s_mov_b32 s47, 0xc2fc0000
	s_movk_i32 s3, 0x1600
	s_movk_i32 s70, 0x3fff
	s_mov_b32 s71, 0x7fffff80
	s_movk_i32 s54, 0x77f
	s_movk_i32 s55, 0xf880
	s_movk_i32 s56, 0x3f7f
	v_mov_b32_e32 v232, 0x3d000000
	v_mov_b32_e32 v233, 0x3c820821
	v_mov_b32_e32 v234, 0x42800000
	v_not_b32_e32 v235, 63
	v_mov_b32_e32 v236, 0x80
	v_mov_b32_e32 v237, 0x7fff8000
	s_mov_b32 s57, s49
	s_barrier
	s_mov_b32 s99, 0
	s_branch .LBB0_112

;     __host__ __device__ bool next(int i, Unit& u) const { return at((long)i * G + c, u); }
;     __host__ __device__ bool next(int i, Unit& u) const { if (i != 0 || c >= cnt) return false; u.pm = pm0 + c / nN; u.pn = c % nN; u.k0 = 0; u.nt = ntk; return true; }
;     ...
;     for (;;) {
;         const bool has_next = S.next(ui + 1, nxt);
;         const char* nA = has_next ? (const char*)g.A + (size_t)nxt.pm * tstep + (size_t)nxt.k0 * (BK * 2) : cA; const char* nB = has_next ? (const char*)g.Bt + (size_t)nxt.pn * tstep + (size_t)nxt.k0 * (BK * 2) : cB;
;         const int nt = cur.nt;
.LBB0_111:
	s_mov_b32 s99, 1
	s_andn2_b64 vcc, exec, s[0:1]
	s_mov_b32 s4, s26
	s_mov_b32 s6, s28
	s_mov_b64 s[36:37], s[34:35]
	s_mov_b64 s[8:9], s[30:31]
	s_cbranch_vccz .LBB0_376

; #define PG8_STAGE(bufoff, gbase, voff) do { _Pragma("unroll") for (int _i = 0; _i < 2; ++_i) \
;         __builtin_amdgcn_global_load_lds((const unsigned*)((const char*)(gbase) + (voff)[_i]), (PG8_LAS unsigned*)(lds + (bufoff) + ldsw + _i * 8192), 16, 0, 0); } while (0)
; #define PG8_STAGEA(bufoff, gbase, voff) do { _Pragma("unroll") for (int _i = 0; _i < 2; ++_i) \
;         __builtin_amdgcn_global_load_lds((const unsigned*)((const char*)(gbase) + (voff)[_i]), (PG8_LAS unsigned*)(lds + (bufoff) + ldsw + _i * 8192), 16, 0, AUXA); } while (0)
; #define PG8_LDA(dst, b, h) do { _Pragma("unroll") for (int m = 0; m < 4; ++m) _Pragma("unroll") for (int k = 0; k < 2; ++k) dst[m][k] = *(const PG8_LAS bf16x8*)(lds + PG8_SA(b, h) + aoff + m * 2048 + k * 1024); } while (0)
; #define PG8_LDB(dst, b, h) do { _Pragma("unroll") for (int n = 0; n < 2; ++n) _Pragma("unroll") for (int k = 0; k < 2; ++k) dst[n][k] = *(const PG8_LAS bf16x8*)(lds + PG8_SB(b, h) + boff + n * 2048 + k * 1024); } while (0)
; #define PG8_MMA(ai, bj, At, Bt) do { __builtin_amdgcn_s_setprio(1); _Pragma("unroll") for (int m = 0; m < 4; ++m) _Pragma("unroll") for (int n = 0; n < 2; ++n) _Pragma("unroll") for (int k = 0; k < 2; ++k) \
;         acc[ai][bj][m][n] = __builtin_amdgcn_mfma_f32_16x16x32_bf16(Bt[n][k], At[m][k], acc[ai][bj][m][n], 0, 0, 0); __builtin_amdgcn_s_setprio(0); } while (0)
; #define PG8_WAIT_V(n) asm volatile("s_waitcnt vmcnt(" #n ")" ::: "memory")
; #define PG8_WAIT_L(n) asm volatile("s_waitcnt lgkmcnt(" #n ")" ::: "memory")
; #define PG8_BAR __builtin_amdgcn_s_barrier()
; #define PG8_SCHED __builtin_amdgcn_sched_barrier(0)
;     ...
;             PG8_LDB(B0, 0, 0); PG8_LDB(B1, 0, 1); PG8_SCHED; PG8_LDA(At, 0, 0); PG8_STAGEA(PG8_SA(1, 1), a1 + hstep, voffA);
;             PG8_WAIT_V(8); PG8_WAIT_L(0); PG8_BAR; PG8_MMA(0, 0, At, B0); PG8_MMA(0, 1, At, B1); PG8_BAR; PG8_SCHED;
;             PG8_LDA(At, 0, 1); PG8_STAGE(PG8_SB(0, 0), b2, voffB); PG8_STAGE(PG8_SB(0, 1), b2 + hstepB, voffB); PG8_STAGEA(PG8_SA(0, 0), a2, voffA);
.Lsprio_0:
.LBB0_119:
	ds_read_b128 v[128:131], v229
	ds_read_b128 v[132:135], v229 offset:1024
	ds_read_b128 v[136:139], v229 offset:2048
	ds_read_b128 v[140:143], v229 offset:3072
	ds_read_b128 v[176:179], v230
	ds_read_b128 v[180:183], v230 offset:1024
	ds_read_b128 v[184:187], v230 offset:2048
	ds_read_b128 v[188:191], v230 offset:3072
	s_add_u32 s36, s8, 0xfffc0080
	s_addc_u32 s37, s9, -1
	s_cmp_eq_u32 s78, 12
	s_cselect_b32 s39, s5, s37
	s_cselect_b32 s38, s7, s36
	s_cselect_b32 s37, s27, s59
	s_cselect_b32 s36, s29, s58
	v_lshl_add_u64 v[172:173], s[8:9], 0, v[164:165]
	s_add_i32 m0, s85, 0xc000
	ds_read_b128 v[192:195], v231
	ds_read_b128 v[196:199], v231 offset:1024
	ds_read_b128 v[238:241], v231 offset:2048
	ds_read_b128 v[242:245], v231 offset:3072
	ds_read_b128 v[246:249], v231 offset:4096
	ds_read_b128 v[250:253], v231 offset:5120
	ds_read_b128 v[210:213], v231 offset:6144
	ds_read_b128 v[214:217], v231 offset:7168
	global_load_lds_dwordx4 v[172:173], off
	v_lshl_add_u64 v[172:173], s[8:9], 0, v[166:167]
	s_add_i32 m0, s85, 0xe000
	s_nop 0
	global_load_lds_dwordx4 v[172:173], off
	s_cmp_lg_u32 s99, 0
	s_cbranch_scc1 .Lfiw_p1_1
	s_waitcnt vmcnt(8)
.Lfiw_p1_1:
	s_waitcnt lgkmcnt(0)
	s_barrier
	s_waitcnt lgkmcnt(0)
	v_mfma_f32_16x16x32_bf16 v[76:79], v[128:131], v[192:195], v[76:79]
	v_mfma_f32_16x16x32_bf16 v[72:75], v[136:139], v[192:195], v[72:75]
	v_mfma_f32_16x16x32_bf16 v[124:127], v[128:131], v[238:241], v[124:127]
	v_mfma_f32_16x16x32_bf16 v[120:123], v[136:139], v[238:241], v[120:123]
	v_mfma_f32_16x16x32_bf16 v[108:111], v[128:131], v[246:249], v[108:111]
	v_mfma_f32_16x16x32_bf16 v[104:107], v[136:139], v[246:249], v[104:107]
	v_mfma_f32_16x16x32_bf16 v[92:95], v[128:131], v[210:213], v[92:95]
	v_mfma_f32_16x16x32_bf16 v[88:91], v[136:139], v[210:213], v[88:91]
	v_mfma_f32_16x16x32_bf16 v[76:79], v[132:135], v[196:199], v[76:79]
	v_mfma_f32_16x16x32_bf16 v[72:75], v[140:143], v[196:199], v[72:75]
	v_mfma_f32_16x16x32_bf16 v[124:127], v[132:135], v[242:245], v[124:127]
	v_mfma_f32_16x16x32_bf16 v[120:123], v[140:143], v[242:245], v[120:123]
	v_mfma_f32_16x16x32_bf16 v[108:111], v[132:135], v[250:253], v[108:111]
	v_mfma_f32_16x16x32_bf16 v[104:107], v[140:143], v[250:253], v[104:107]
	v_mfma_f32_16x16x32_bf16 v[92:95], v[132:135], v[214:217], v[92:95]
	v_mfma_f32_16x16x32_bf16 v[88:91], v[140:143], v[214:217], v[88:91]
	v_mfma_f32_16x16x32_bf16 v[52:55], v[176:179], v[192:195], v[52:55]
	v_mfma_f32_16x16x32_bf16 v[48:51], v[184:187], v[192:195], v[48:51]
	v_mfma_f32_16x16x32_bf16 v[116:119], v[176:179], v[238:241], v[116:119]
	v_mfma_f32_16x16x32_bf16 v[112:115], v[184:187], v[238:241], v[112:115]
	v_mfma_f32_16x16x32_bf16 v[100:103], v[176:179], v[246:249], v[100:103]
	v_mfma_f32_16x16x32_bf16 v[96:99], v[184:187], v[246:249], v[96:99]
	v_mfma_f32_16x16x32_bf16 v[84:87], v[176:179], v[210:213], v[84:87]
	v_mfma_f32_16x16x32_bf16 v[80:83], v[184:187], v[210:213], v[80:83]
	v_mfma_f32_16x16x32_bf16 v[52:55], v[180:183], v[196:199], v[52:55]
	v_mfma_f32_16x16x32_bf16 v[48:51], v[188:191], v[196:199], v[48:51]
	v_mfma_f32_16x16x32_bf16 v[116:119], v[180:183], v[242:245], v[116:119]
	v_mfma_f32_16x16x32_bf16 v[112:115], v[188:191], v[242:245], v[112:115]
	v_mfma_f32_16x16x32_bf16 v[100:103], v[180:183], v[250:253], v[100:103]
	v_mfma_f32_16x16x32_bf16 v[96:99], v[188:191], v[250:253], v[96:99]
	v_mfma_f32_16x16x32_bf16 v[84:87], v[180:183], v[214:217], v[84:87]
	v_mfma_f32_16x16x32_bf16 v[80:83], v[188:191], v[214:217], v[80:83]
	s_barrier
	s_add_i32 s79, s73, s67
	v_lshl_add_u64 v[172:173], s[36:37], 0, v[146:147]
	s_mov_b32 m0, s79
	ds_read_b128 v[192:195], v231 offset:16384
	ds_read_b128 v[196:199], v231 offset:17408
	ds_read_b128 v[210:213], v231 offset:18432
	ds_read_b128 v[214:217], v231 offset:19456
	ds_read_b128 v[238:241], v231 offset:20480
	ds_read_b128 v[242:245], v231 offset:21504
	ds_read_b128 v[246:249], v231 offset:22528
	ds_read_b128 v[250:253], v231 offset:23552
	global_load_lds_dwordx4 v[172:173], off
	s_add_i32 m0, s79, 0x2000
	s_add_u32 s80, s36, 0x10000
	v_lshl_add_u64 v[202:203], s[36:37], 0, v[150:151]
	s_addc_u32 s81, s37, 0
	s_add_i32 s79, s46, s67
	global_load_lds_dwordx4 v[202:203], off
	v_lshl_add_u64 v[204:205], s[80:81], 0, v[146:147]
	s_mov_b32 m0, s79
	v_lshl_add_u64 v[206:207], s[38:39], 0, v[148:149]
	global_load_lds_dwordx4 v[204:205], off
	v_lshl_add_u64 v[204:205], s[80:81], 0, v[150:151]
	s_add_i32 m0, s79, 0x2000
	s_nop 0
	global_load_lds_dwordx4 v[204:205], off
	v_lshl_add_u64 v[204:205], s[38:39], 0, v[144:145]
	s_mov_b32 m0, s85
	s_nop 0
	global_load_lds_dwordx4 v[204:205], off
	s_mov_b32 m0, s86
	s_nop 0
	global_load_lds_dwordx4 v[206:207], off
	s_cmp_lg_u32 s99, 0
	s_cbranch_scc1 .Lfiw_p1_0
	s_waitcnt vmcnt(8)
; #define PG8_STAGE(bufoff, gbase, voff) do { _Pragma("unroll") for (int _i = 0; _i < 2; ++_i) \
;         __builtin_amdgcn_global_load_lds((const unsigned*)((const char*)(gbase) + (voff)[_i]), (PG8_LAS unsigned*)(lds + (bufoff) + ldsw + _i * 8192), 16, 0, 0); } while (0)
; #define PG8_STAGEA(bufoff, gbase, voff) do { _Pragma("unroll") for (int _i = 0; _i < 2; ++_i) \
;         __builtin_amdgcn_global_load_lds((const unsigned*)((const char*)(gbase) + (voff)[_i]), (PG8_LAS unsigned*)(lds + (bufoff) + ldsw + _i * 8192), 16, 0, AUXA); } while (0)
; #define PG8_LDA(dst, b, h) do { _Pragma("unroll") for (int m = 0; m < 4; ++m) _Pragma("unroll") for (int k = 0; k < 2; ++k) dst[m][k] = *(const PG8_LAS bf16x8*)(lds + PG8_SA(b, h) + aoff + m * 2048 + k * 1024); } while (0)
; #define PG8_LDB(dst, b, h) do { _Pragma("unroll") for (int n = 0; n < 2; ++n) _Pragma("unroll") for (int k = 0; k < 2; ++k) dst[n][k] = *(const PG8_LAS bf16x8*)(lds + PG8_SB(b, h) + boff + n * 2048 + k * 1024); } while (0)
; #define PG8_MMA(ai, bj, At, Bt) do { __builtin_amdgcn_s_setprio(1); _Pragma("unroll") for (int m = 0; m < 4; ++m) _Pragma("unroll") for (int n = 0; n < 2; ++n) _Pragma("unroll") for (int k = 0; k < 2; ++k) \
;         acc[ai][bj][m][n] = __builtin_amdgcn_mfma_f32_16x16x32_bf16(Bt[n][k], At[m][k], acc[ai][bj][m][n], 0, 0, 0); __builtin_amdgcn_s_setprio(0); } while (0)
; #define PG8_WAIT_V(n) asm volatile("s_waitcnt vmcnt(" #n ")" ::: "memory")
; #define PG8_WAIT_L(n) asm volatile("s_waitcnt lgkmcnt(" #n ")" ::: "memory")
; #define PG8_BAR __builtin_amdgcn_s_barrier()
; #define PG8_SCHED __builtin_amdgcn_sched_barrier(0)
;     ...
;             PG8_LDA(At, 0, 1); PG8_STAGE(PG8_SB(0, 0), b2, voffB); PG8_STAGE(PG8_SB(0, 1), b2 + hstepB, voffB); PG8_STAGEA(PG8_SA(0, 0), a2, voffA);
;             PG8_WAIT_V(8); PG8_WAIT_L(0); PG8_BAR; PG8_MMA(1, 0, At, B0); PG8_MMA(1, 1, At, B1); PG8_BAR; PG8_SCHED;
;             PG8_LDB(B0, 1, 0); PG8_LDB(B1, 1, 1); PG8_SCHED; PG8_LDA(At, 1, 0); PG8_STAGEA(PG8_SA(0, 1), a2 + hstep, voffA);
;             PG8_WAIT_V(8); PG8_WAIT_L(0); PG8_BAR; PG8_MMA(0, 0, At, B0); PG8_MMA(0, 1, At, B1); PG8_BAR; PG8_SCHED;
.Lfiw_p1_0:
	s_waitcnt lgkmcnt(0)
	s_barrier
	s_waitcnt lgkmcnt(0)
	v_mfma_f32_16x16x32_bf16 v[68:71], v[128:131], v[192:195], v[68:71]
	v_mfma_f32_16x16x32_bf16 v[64:67], v[136:139], v[192:195], v[64:67]
	v_mfma_f32_16x16x32_bf16 v[44:47], v[128:131], v[210:213], v[44:47]
	v_mfma_f32_16x16x32_bf16 v[40:43], v[136:139], v[210:213], v[40:43]
	v_mfma_f32_16x16x32_bf16 v[28:31], v[128:131], v[238:241], v[28:31]
	v_mfma_f32_16x16x32_bf16 v[24:27], v[136:139], v[238:241], v[24:27]
	v_mfma_f32_16x16x32_bf16 v[12:15], v[128:131], v[246:249], v[12:15]
	v_mfma_f32_16x16x32_bf16 v[8:11], v[136:139], v[246:249], v[8:11]
	v_mfma_f32_16x16x32_bf16 v[68:71], v[132:135], v[196:199], v[68:71]
	v_mfma_f32_16x16x32_bf16 v[64:67], v[140:143], v[196:199], v[64:67]
	v_mfma_f32_16x16x32_bf16 v[44:47], v[132:135], v[214:217], v[44:47]
	v_mfma_f32_16x16x32_bf16 v[40:43], v[140:143], v[214:217], v[40:43]
	v_mfma_f32_16x16x32_bf16 v[28:31], v[132:135], v[242:245], v[28:31]
	v_mfma_f32_16x16x32_bf16 v[24:27], v[140:143], v[242:245], v[24:27]
	v_mfma_f32_16x16x32_bf16 v[12:15], v[132:135], v[250:253], v[12:15]
	v_mfma_f32_16x16x32_bf16 v[8:11], v[140:143], v[250:253], v[8:11]
	v_mfma_f32_16x16x32_bf16 v[60:63], v[176:179], v[192:195], v[60:63]
	v_mfma_f32_16x16x32_bf16 v[56:59], v[184:187], v[192:195], v[56:59]
	v_mfma_f32_16x16x32_bf16 v[36:39], v[176:179], v[210:213], v[36:39]
	v_mfma_f32_16x16x32_bf16 v[32:35], v[184:187], v[210:213], v[32:35]
	v_mfma_f32_16x16x32_bf16 v[20:23], v[176:179], v[238:241], v[20:23]
	v_mfma_f32_16x16x32_bf16 v[16:19], v[184:187], v[238:241], v[16:19]
	v_mfma_f32_16x16x32_bf16 v[4:7], v[176:179], v[246:249], v[4:7]
	v_mfma_f32_16x16x32_bf16 v[0:3], v[184:187], v[246:249], v[0:3]
	v_mfma_f32_16x16x32_bf16 v[60:63], v[180:183], v[196:199], v[60:63]
	v_mfma_f32_16x16x32_bf16 v[56:59], v[188:191], v[196:199], v[56:59]
	v_mfma_f32_16x16x32_bf16 v[36:39], v[180:183], v[214:217], v[36:39]
	v_mfma_f32_16x16x32_bf16 v[32:35], v[188:191], v[214:217], v[32:35]
	v_mfma_f32_16x16x32_bf16 v[20:23], v[180:183], v[242:245], v[20:23]
	v_mfma_f32_16x16x32_bf16 v[16:19], v[188:191], v[242:245], v[16:19]
	v_mfma_f32_16x16x32_bf16 v[4:7], v[180:183], v[250:253], v[4:7]
	v_mfma_f32_16x16x32_bf16 v[0:3], v[188:191], v[250:253], v[0:3]
	s_barrier
	s_add_i32 s79, 0, 0x18000
	s_add_i32 s80, 0, 0x1c000
	v_add_u32_e32 v140, s79, v226
	v_add_u32_e32 v152, s80, v226
	ds_read_b128 v[128:131], v140
	ds_read_b128 v[132:135], v140 offset:1024
	ds_read_b128 v[136:139], v140 offset:2048
	ds_read_b128 v[140:143], v140 offset:3072
	ds_read_b128 v[176:179], v152
	ds_read_b128 v[180:183], v152 offset:1024
	ds_read_b128 v[184:187], v152 offset:2048
	ds_read_b128 v[188:191], v152 offset:3072
	s_add_u32 s38, s38, 0x40000
	s_addc_u32 s39, s39, 0
	s_mov_b32 m0, s87
	v_lshl_add_u64 v[218:219], s[38:39], 0, v[144:145]
	ds_read_b128 v[192:195], v231 offset:32768
	ds_read_b128 v[196:199], v231 offset:33792
	ds_read_b128 v[210:213], v231 offset:34816
	ds_read_b128 v[214:217], v231 offset:35840
	ds_read_b128 v[238:241], v231 offset:36864
	ds_read_b128 v[242:245], v231 offset:37888
	ds_read_b128 v[246:249], v231 offset:38912
	ds_read_b128 v[250:253], v231 offset:39936
	global_load_lds_dwordx4 v[218:219], off
	v_lshl_add_u64 v[218:219], s[38:39], 0, v[148:149]
	s_mov_b32 m0, s88
	s_nop 0
	global_load_lds_dwordx4 v[218:219], off
	s_mov_b32 s99, 0
	s_waitcnt vmcnt(8)
	s_waitcnt lgkmcnt(0)
	s_barrier
	s_waitcnt lgkmcnt(0)
	v_mfma_f32_16x16x32_bf16 v[76:79], v[128:131], v[192:195], v[76:79]
	v_mfma_f32_16x16x32_bf16 v[72:75], v[136:139], v[192:195], v[72:75]
	v_mfma_f32_16x16x32_bf16 v[124:127], v[128:131], v[210:213], v[124:127]
	v_mfma_f32_16x16x32_bf16 v[120:123], v[136:139], v[210:213], v[120:123]
	v_mfma_f32_16x16x32_bf16 v[108:111], v[128:131], v[238:241], v[108:111]
	v_mfma_f32_16x16x32_bf16 v[104:107], v[136:139], v[238:241], v[104:107]
	v_mfma_f32_16x16x32_bf16 v[92:95], v[128:131], v[246:249], v[92:95]
	v_mfma_f32_16x16x32_bf16 v[88:91], v[136:139], v[246:249], v[88:91]
	v_mfma_f32_16x16x32_bf16 v[76:79], v[132:135], v[196:199], v[76:79]
	v_mfma_f32_16x16x32_bf16 v[72:75], v[140:143], v[196:199], v[72:75]
	v_mfma_f32_16x16x32_bf16 v[124:127], v[132:135], v[214:217], v[124:127]
	v_mfma_f32_16x16x32_bf16 v[120:123], v[140:143], v[214:217], v[120:123]
	v_mfma_f32_16x16x32_bf16 v[108:111], v[132:135], v[242:245], v[108:111]
	v_mfma_f32_16x16x32_bf16 v[104:107], v[140:143], v[242:245], v[104:107]
	v_mfma_f32_16x16x32_bf16 v[92:95], v[132:135], v[250:253], v[92:95]
	v_mfma_f32_16x16x32_bf16 v[88:91], v[140:143], v[250:253], v[88:91]
	v_mfma_f32_16x16x32_bf16 v[52:55], v[176:179], v[192:195], v[52:55]
	v_mfma_f32_16x16x32_bf16 v[48:51], v[184:187], v[192:195], v[48:51]
	v_mfma_f32_16x16x32_bf16 v[116:119], v[176:179], v[210:213], v[116:119]
	v_mfma_f32_16x16x32_bf16 v[112:115], v[184:187], v[210:213], v[112:115]
	v_mfma_f32_16x16x32_bf16 v[100:103], v[176:179], v[238:241], v[100:103]
	v_mfma_f32_16x16x32_bf16 v[96:99], v[184:187], v[238:241], v[96:99]
	v_mfma_f32_16x16x32_bf16 v[84:87], v[176:179], v[246:249], v[84:87]
	v_mfma_f32_16x16x32_bf16 v[80:83], v[184:187], v[246:249], v[80:83]
	v_mfma_f32_16x16x32_bf16 v[52:55], v[180:183], v[196:199], v[52:55]
	v_mfma_f32_16x16x32_bf16 v[48:51], v[188:191], v[196:199], v[48:51]
	v_mfma_f32_16x16x32_bf16 v[116:119], v[180:183], v[214:217], v[116:119]
	v_mfma_f32_16x16x32_bf16 v[112:115], v[188:191], v[214:217], v[112:115]
	v_mfma_f32_16x16x32_bf16 v[100:103], v[180:183], v[242:245], v[100:103]
	v_mfma_f32_16x16x32_bf16 v[96:99], v[188:191], v[242:245], v[96:99]
	v_mfma_f32_16x16x32_bf16 v[84:87], v[180:183], v[250:253], v[84:87]
	v_mfma_f32_16x16x32_bf16 v[80:83], v[188:191], v[250:253], v[80:83]
	s_barrier
; #define PG8_STAGE(bufoff, gbase, voff) do { _Pragma("unroll") for (int _i = 0; _i < 2; ++_i) \
;         __builtin_amdgcn_global_load_lds((const unsigned*)((const char*)(gbase) + (voff)[_i]), (PG8_LAS unsigned*)(lds + (bufoff) + ldsw + _i * 8192), 16, 0, 0); } while (0)
; #define PG8_STAGEA(bufoff, gbase, voff) do { _Pragma("unroll") for (int _i = 0; _i < 2; ++_i) \
;         __builtin_amdgcn_global_load_lds((const unsigned*)((const char*)(gbase) + (voff)[_i]), (PG8_LAS unsigned*)(lds + (bufoff) + ldsw + _i * 8192), 16, 0, AUXA); } while (0)
; #define PG8_BAR __builtin_amdgcn_s_barrier()
;     ...
;             PG8_LDA(At, 1, 1); PG8_STAGE(PG8_SB(1, 0), b3, voffB); PG8_STAGE(PG8_SB(1, 1), b3 + hstepB, voffB); PG8_STAGEA(PG8_SA(1, 0), a3, voffA);
;             PG8_WAIT_V(8); PG8_WAIT_L(0); PG8_BAR; PG8_MMA(1, 0, At, B0); PG8_MMA(1, 1, At, B1); PG8_BAR; PG8_SCHED;
;             } else {
;             PG8_LDB(B0, 0, 0); PG8_SCHED; PG8_LDA(At, 0, 0); PG8_STAGEA(PG8_SA(1, 1), a1 + hstep, voffA);
;             PG8_WAIT_L(8); PG8_BAR; PG8_WAIT_L(0); PG8_MMA(0, 0, At, B0); PG8_BAR; PG8_SCHED;
;             PG8_LDB(B1, 0, 1); PG8_STAGE(PG8_SB(0, 0), b2, voffB);
;             PG8_BAR; PG8_WAIT_L(0); PG8_MMA(0, 1, At, B1); PG8_BAR;
;             PG8_LDA(At, 0, 1); PG8_STAGEA(PG8_SA(0, 0), a2, voffA);
;             PG8_BAR; PG8_WAIT_L(0); PG8_MMA(1, 0, At, B0); PG8_BAR; PG8_SCHED;
;             PG8_STAGE(PG8_SB(0, 1), b2 + hstepB, voffB);
;             PG8_WAIT_V(6); PG8_BAR; PG8_MMA(1, 1, At, B1); PG8_BAR;
;             PG8_LDB(B0, 1, 0); PG8_SCHED; PG8_LDA(At, 1, 0); PG8_STAGEA(PG8_SA(0, 1), a2 + hstep, voffA);
;             PG8_WAIT_L(8); PG8_BAR; PG8_WAIT_L(0); PG8_MMA(0, 0, At, B0); PG8_BAR; PG8_SCHED;
;             PG8_LDB(B1, 1, 1); PG8_STAGE(PG8_SB(1, 0), b3, voffB);
;             PG8_BAR; PG8_WAIT_L(0); PG8_MMA(0, 1, At, B1); PG8_BAR;
;             PG8_LDA(At, 1, 1); PG8_STAGEA(PG8_SA(1, 0), a3, voffA);
;             PG8_BAR; PG8_WAIT_L(0); PG8_MMA(1, 0, At, B0); PG8_BAR; PG8_SCHED;
;             PG8_STAGE(PG8_SB(1, 1), b3 + hstepB, voffB);
;             PG8_WAIT_V(6); PG8_BAR; PG8_MMA(1, 1, At, B1); PG8_BAR;
;             }
;         }
;         if constexpr (ALIGN_EPI) { if (wr == 0) PG8_BAR; }
;         if constexpr (!Epi::AFTER_DRAIN) { if (!(Epi::LAST_FUSED && !has_next)) { E(acc, cur, wr, wc, fr, fq); S.done(cur); } }
;         if (!has_next) break;
	s_add_i32 s38, s79, s67
	v_lshl_add_u64 v[172:173], v[172:173], 0, s[16:17]
	s_mov_b32 m0, s38
	ds_read_b128 v[192:195], v231 offset:49152
	ds_read_b128 v[196:199], v231 offset:50176
	ds_read_b128 v[210:213], v231 offset:51200
	ds_read_b128 v[214:217], v231 offset:52224
	ds_read_b128 v[238:241], v231 offset:53248
	ds_read_b128 v[242:245], v231 offset:54272
	ds_read_b128 v[246:249], v231 offset:55296
	ds_read_b128 v[250:253], v231 offset:56320
	global_load_lds_dwordx4 v[172:173], off
	s_add_i32 m0, s38, 0x2000
	s_add_u32 s36, s36, 0x10080
	v_lshl_add_u64 v[172:173], v[202:203], 0, s[16:17]
	s_addc_u32 s37, s37, 0
	s_add_i32 s38, s80, s67
	global_load_lds_dwordx4 v[172:173], off
	v_lshl_add_u64 v[172:173], s[36:37], 0, v[146:147]
	s_mov_b32 m0, s38
	s_nop 0
	global_load_lds_dwordx4 v[172:173], off
	v_lshl_add_u64 v[172:173], s[36:37], 0, v[150:151]
	s_add_i32 m0, s38, 0x2000
	s_nop 0
	global_load_lds_dwordx4 v[172:173], off
	v_lshl_add_u64 v[172:173], v[204:205], 0, s[16:17]
	s_mov_b32 m0, s89
	s_nop 0
	global_load_lds_dwordx4 v[172:173], off
	v_lshl_add_u64 v[172:173], v[206:207], 0, s[16:17]
	s_mov_b32 m0, s90
	s_nop 0
	global_load_lds_dwordx4 v[172:173], off
	s_waitcnt vmcnt(8)
	s_waitcnt lgkmcnt(0)
	s_barrier
	s_waitcnt lgkmcnt(0)
	v_mfma_f32_16x16x32_bf16 v[68:71], v[128:131], v[192:195], v[68:71]
	v_mfma_f32_16x16x32_bf16 v[64:67], v[136:139], v[192:195], v[64:67]
	v_mfma_f32_16x16x32_bf16 v[44:47], v[128:131], v[210:213], v[44:47]
	v_mfma_f32_16x16x32_bf16 v[40:43], v[136:139], v[210:213], v[40:43]
	v_mfma_f32_16x16x32_bf16 v[28:31], v[128:131], v[238:241], v[28:31]
	v_mfma_f32_16x16x32_bf16 v[24:27], v[136:139], v[238:241], v[24:27]
	v_mfma_f32_16x16x32_bf16 v[12:15], v[128:131], v[246:249], v[12:15]
	v_mfma_f32_16x16x32_bf16 v[8:11], v[136:139], v[246:249], v[8:11]
	v_mfma_f32_16x16x32_bf16 v[68:71], v[132:135], v[196:199], v[68:71]
	v_mfma_f32_16x16x32_bf16 v[64:67], v[140:143], v[196:199], v[64:67]
	v_mfma_f32_16x16x32_bf16 v[44:47], v[132:135], v[214:217], v[44:47]
	v_mfma_f32_16x16x32_bf16 v[40:43], v[140:143], v[214:217], v[40:43]
	v_mfma_f32_16x16x32_bf16 v[28:31], v[132:135], v[242:245], v[28:31]
	v_mfma_f32_16x16x32_bf16 v[24:27], v[140:143], v[242:245], v[24:27]
	v_mfma_f32_16x16x32_bf16 v[12:15], v[132:135], v[250:253], v[12:15]
	v_mfma_f32_16x16x32_bf16 v[8:11], v[140:143], v[250:253], v[8:11]
	v_mfma_f32_16x16x32_bf16 v[60:63], v[176:179], v[192:195], v[60:63]
	v_mfma_f32_16x16x32_bf16 v[56:59], v[184:187], v[192:195], v[56:59]
	v_mfma_f32_16x16x32_bf16 v[36:39], v[176:179], v[210:213], v[36:39]
	v_mfma_f32_16x16x32_bf16 v[32:35], v[184:187], v[210:213], v[32:35]
	v_mfma_f32_16x16x32_bf16 v[20:23], v[176:179], v[238:241], v[20:23]
	v_mfma_f32_16x16x32_bf16 v[16:19], v[184:187], v[238:241], v[16:19]
	v_mfma_f32_16x16x32_bf16 v[4:7], v[176:179], v[246:249], v[4:7]
	v_mfma_f32_16x16x32_bf16 v[0:3], v[184:187], v[246:249], v[0:3]
	v_mfma_f32_16x16x32_bf16 v[60:63], v[180:183], v[196:199], v[60:63]
	v_mfma_f32_16x16x32_bf16 v[56:59], v[188:191], v[196:199], v[56:59]
	v_mfma_f32_16x16x32_bf16 v[36:39], v[180:183], v[214:217], v[36:39]
	v_mfma_f32_16x16x32_bf16 v[32:35], v[188:191], v[214:217], v[32:35]
	v_mfma_f32_16x16x32_bf16 v[20:23], v[180:183], v[242:245], v[20:23]
	v_mfma_f32_16x16x32_bf16 v[16:19], v[188:191], v[242:245], v[16:19]
	v_mfma_f32_16x16x32_bf16 v[4:7], v[180:183], v[250:253], v[4:7]
	v_mfma_f32_16x16x32_bf16 v[0:3], v[188:191], v[250:253], v[0:3]
	s_barrier
	s_add_i32 s78, s78, 2
	s_add_u32 s8, s8, 0x100
	s_addc_u32 s9, s9, 0
	s_add_u32 s58, s58, 0x100
	s_addc_u32 s59, s59, 0
	s_cmp_gt_u32 s78, 13
	s_cbranch_scc0 .LBB0_119
	s_setprio 0
	s_and_b64 vcc, exec, s[18:19]
	s_cbranch_vccz .LBB0_122
	s_barrier
